# first-barrier census: the 16 per-XCC counter loads issued together instead of one load per full wait
# baseline (speedup 1.0000x reference)
; __device__ __forceinline__ unsigned xb_ld(unsigned* p)              { return __hip_atomic_load(p, __ATOMIC_RELAXED, __HIP_MEMORY_SCOPE_AGENT); }
; __device__ __forceinline__ void xcd_barrier_complete(unsigned* bar, unsigned x, unsigned& nloc, unsigned& nx) {
;     const unsigned G = gridDim.x * gridDim.y * gridDim.z;
;     unsigned sum, cnt, mine, sp = 0u;
;     for (;;) {
;         sum = 0u; cnt = 0u; mine = 0u;
; #pragma unroll
;         for (unsigned j = 0; j < 16; ++j) { const unsigned c = xb_ld(&bar[XB_XCNT(j)]); sum += c; cnt += (c > 0u) ? 1u : 0u; mine = (j == x) ? c : mine; }
;         if (sum == G) break;
;         __builtin_amdgcn_s_sleep(1);
;         if ((++sp & 255u) == 0u) { if (xb_ld(&bar[XB_TMO])) break; if (sp > XB_SPIN_CAP) { atomicAdd(&bar[XB_TMO], 1u); break; } }
;     }
;     nloc = mine > 0u ? mine : 1u; nx = cnt > 0u ? cnt : 1u;
; }
.LBB0_555:
	v_readlane_b32 s11, v254, 6
	s_mov_b64 s[38:39], -1
	s_waitcnt lgkmcnt(0)
	v_readlane_b32 s12, v254, 9
	v_readlane_b32 s13, v254, 10
	s_nop 4
	global_load_dword v0, v2, s[12:13] sc1
	v_readlane_b32 s12, v254, 11
	v_readlane_b32 s13, v254, 12
	s_nop 4
	global_load_dword v1, v2, s[12:13] sc1
	v_readlane_b32 s12, v254, 13
	v_readlane_b32 s13, v254, 14
	s_nop 4
	global_load_dword v3, v2, s[12:13] sc1
	v_readlane_b32 s12, v254, 15
	v_readlane_b32 s13, v254, 16
	s_nop 4
	global_load_dword v4, v2, s[12:13] sc1
	v_readlane_b32 s12, v254, 17
	v_readlane_b32 s13, v254, 18
	s_nop 4
	global_load_dword v5, v2, s[12:13] sc1
	v_readlane_b32 s12, v254, 19
	v_readlane_b32 s13, v254, 20
	s_nop 4
	global_load_dword v6, v2, s[12:13] sc1
	v_readlane_b32 s12, v254, 21
	v_readlane_b32 s13, v254, 22
	s_nop 4
	global_load_dword v7, v2, s[12:13] sc1
	v_readlane_b32 s12, v254, 23
	v_readlane_b32 s13, v254, 24
	s_nop 4
	global_load_dword v8, v2, s[12:13] sc1
	v_readlane_b32 s12, v254, 25
	v_readlane_b32 s13, v254, 26
	s_nop 4
	global_load_dword v9, v2, s[12:13] sc1
	v_readlane_b32 s12, v254, 27
	v_readlane_b32 s13, v254, 28
	s_nop 4
	global_load_dword v10, v2, s[12:13] sc1
	v_readlane_b32 s12, v254, 29
	v_readlane_b32 s13, v254, 30
	s_nop 4
	global_load_dword v11, v2, s[12:13] sc1
	v_readlane_b32 s12, v254, 31
	v_readlane_b32 s13, v254, 32
	s_nop 4
	global_load_dword v12, v2, s[12:13] sc1
	v_readlane_b32 s12, v254, 33
	v_readlane_b32 s13, v254, 34
	s_nop 4
	global_load_dword v13, v2, s[12:13] sc1
	v_readlane_b32 s12, v254, 35
	v_readlane_b32 s13, v254, 36
	s_nop 4
	global_load_dword v14, v2, s[12:13] sc1
	v_readlane_b32 s12, v254, 37
	v_readlane_b32 s13, v254, 38
	s_nop 4
	global_load_dword v15, v2, s[12:13] sc1
	v_readlane_b32 s12, v254, 39
	v_readlane_b32 s13, v254, 40
	s_nop 4
	global_load_dword v16, v2, s[12:13] sc1
	s_mov_b64 s[12:13], -1
	s_waitcnt vmcnt(0)
	v_add_u32_e32 v17, v1, v0
	v_add_u32_e32 v17, v17, v3
	v_add_u32_e32 v17, v17, v4
	v_add_u32_e32 v17, v17, v5
	v_add_u32_e32 v17, v17, v6
	v_add_u32_e32 v17, v17, v7
	v_add_u32_e32 v17, v17, v8
	v_add_u32_e32 v17, v17, v9
	v_add_u32_e32 v17, v17, v10
	v_add_u32_e32 v17, v17, v11
	v_add_u32_e32 v17, v17, v12
	v_add_u32_e32 v17, v17, v13
	v_add_u32_e32 v17, v17, v14
	v_add_u32_e32 v17, v17, v15
	v_add_u32_e32 v17, v17, v16
	v_cmp_eq_u32_e32 vcc, s11, v17
	s_cbranch_vccnz .LBB0_554
	s_and_b32 s11, s10, 0xff
	s_cmp_eq_u32 s11, 0
	s_mov_b64 s[40:41], -1
	s_sleep 1
	s_cbranch_scc0 .LBB0_559
	v_readlane_b32 s12, v254, 7
	v_readlane_b32 s13, v254, 8
	s_nop 4
	global_load_dword v17, v2, s[12:13] sc1
	s_waitcnt vmcnt(0)
	v_cmp_eq_u32_e32 vcc, 0, v17
	s_cbranch_vccnz .LBB0_561
	s_mov_b64 s[40:41], 0
	s_mov_b64 s[12:13], -1
